# attention: row-max cross-half exchange via v_permlane32_swap instead of ds_bpermute, stream-1 QK first-batch LDS reads hoisted above the mid-tile K store; on top of unrolled scan
# speedup vs baseline: 1.0261x; 1.0085x over previous
; template <int NS, int SI>
; __device__ __forceinline__ void attn_stream(const unsigned char* kbase, const unsigned char* vbase, const unsigned char* q_rd, bool mask_tail, int last_valid, int hh, float sc,
;                                             f32x16 (&O)[4], float& mrun, float& lrun) {
;     ...
;     f32x2 ls2 = {0.f, 0.f};
;     const f32x2 sc2 = {sc, sc}, mn2 = {mn, mn};
; #pragma unroll
;     for (int r = 0; r < 16; r += 2) {
;         const f32x2 t0 = (f32x2){S0[r], S0[r + 1]} * sc2 - mn2, t1 = (f32x2){S1[r], S1[r + 1]} * sc2 - mn2;
;         const f32x2 p0 = {__builtin_amdgcn_exp2f(t0.x), __builtin_amdgcn_exp2f(t0.y)}, p1 = {__builtin_amdgcn_exp2f(t1.x), __builtin_amdgcn_exp2f(t1.y)};
;         S0[r] = p0.x; S0[r + 1] = p0.y; S1[r] = p1.x; S1[r + 1] = p1.y; ls2 += p0 + p1;
;     }
;     lrun = lrun * alpha + (ls2.x + ls2.y);
;     if (__any(alpha != 1.0f)) {
; #pragma unroll
;         for (int d = 0; d < 4; ++d) O[d] = O[d] * alpha;
;     }
.LBB0_1167:
	v_pk_fma_f32 v[128:129], v[128:129], s[58:59], v[200:201] op_sel_hi:[1,0,0] neg_lo:[0,0,1] neg_hi:[0,0,1]
	v_pk_fma_f32 v[144:145], v[144:145], s[58:59], v[200:201] op_sel_hi:[1,0,0] neg_lo:[0,0,1] neg_hi:[0,0,1]
	v_exp_f32_e32 v232, v128
	v_exp_f32_e32 v233, v129
	v_exp_f32_e32 v144, v144
	v_exp_f32_e32 v145, v145
	v_pk_fma_f32 v[128:129], v[130:131], s[58:59], v[200:201] op_sel_hi:[1,0,0] neg_lo:[0,0,1] neg_hi:[0,0,1]
	v_pk_fma_f32 v[130:131], v[146:147], s[58:59], v[200:201] op_sel_hi:[1,0,0] neg_lo:[0,0,1] neg_hi:[0,0,1]
	v_exp_f32_e32 v146, v128
	v_exp_f32_e32 v147, v129
	v_exp_f32_e32 v234, v130
	v_exp_f32_e32 v235, v131
	v_pk_fma_f32 v[132:133], v[132:133], s[58:59], v[200:201] op_sel_hi:[1,0,0] neg_lo:[0,0,1] neg_hi:[0,0,1]
	v_pk_fma_f32 v[148:149], v[148:149], s[58:59], v[200:201] op_sel_hi:[1,0,0] neg_lo:[0,0,1] neg_hi:[0,0,1]
	v_exp_f32_e32 v236, v132
	v_exp_f32_e32 v237, v133
	v_exp_f32_e32 v148, v148
	v_exp_f32_e32 v149, v149
	v_pk_fma_f32 v[132:133], v[134:135], s[58:59], v[200:201] op_sel_hi:[1,0,0] neg_lo:[0,0,1] neg_hi:[0,0,1]
	v_pk_fma_f32 v[134:135], v[150:151], s[58:59], v[200:201] op_sel_hi:[1,0,0] neg_lo:[0,0,1] neg_hi:[0,0,1]
	v_exp_f32_e32 v150, v132
	v_exp_f32_e32 v151, v133
	v_exp_f32_e32 v238, v134
	v_exp_f32_e32 v239, v135
	v_pk_fma_f32 v[132:133], v[136:137], s[58:59], v[200:201] op_sel_hi:[1,0,0] neg_lo:[0,0,1] neg_hi:[0,0,1]
	v_pk_fma_f32 v[134:135], v[152:153], s[58:59], v[200:201] op_sel_hi:[1,0,0] neg_lo:[0,0,1] neg_hi:[0,0,1]
	v_pk_add_f32 v[128:129], v[144:145], v[232:233]
	v_exp_f32_e32 v152, v132
	v_exp_f32_e32 v153, v133
	v_exp_f32_e32 v240, v134
	v_exp_f32_e32 v241, v135
	v_pk_fma_f32 v[132:133], v[138:139], s[58:59], v[200:201] op_sel_hi:[1,0,0] neg_lo:[0,0,1] neg_hi:[0,0,1]
	v_pk_fma_f32 v[134:135], v[154:155], s[58:59], v[200:201] op_sel_hi:[1,0,0] neg_lo:[0,0,1] neg_hi:[0,0,1]
	v_pk_add_f32 v[128:129], v[128:129], 0 op_sel_hi:[1,0]
	v_pk_add_f32 v[130:131], v[234:235], v[146:147]
	v_exp_f32_e32 v154, v132
	v_exp_f32_e32 v155, v133
	v_exp_f32_e32 v242, v134
	v_exp_f32_e32 v243, v135
	v_pk_fma_f32 v[132:133], v[140:141], s[58:59], v[200:201] op_sel_hi:[1,0,0] neg_lo:[0,0,1] neg_hi:[0,0,1]
	v_pk_fma_f32 v[134:135], v[156:157], s[58:59], v[200:201] op_sel_hi:[1,0,0] neg_lo:[0,0,1] neg_hi:[0,0,1]
	v_pk_add_f32 v[128:129], v[130:131], v[128:129]
	v_pk_add_f32 v[130:131], v[148:149], v[236:237]
	v_exp_f32_e32 v140, v132
	v_exp_f32_e32 v141, v133
	v_exp_f32_e32 v156, v134
	v_exp_f32_e32 v157, v135
	v_pk_fma_f32 v[132:133], v[142:143], s[58:59], v[200:201] op_sel_hi:[1,0,0] neg_lo:[0,0,1] neg_hi:[0,0,1]
	v_pk_fma_f32 v[134:135], v[158:159], s[58:59], v[200:201] op_sel_hi:[1,0,0] neg_lo:[0,0,1] neg_hi:[0,0,1]
	v_pk_add_f32 v[128:129], v[130:131], v[128:129]
	v_pk_add_f32 v[130:131], v[238:239], v[150:151]
	v_exp_f32_e32 v142, v132
	v_exp_f32_e32 v143, v133
	v_exp_f32_e32 v158, v134
	v_exp_f32_e32 v159, v135
	v_pk_add_f32 v[128:129], v[130:131], v[128:129]
	v_pk_add_f32 v[130:131], v[240:241], v[152:153]
	s_nop 0
	v_pk_add_f32 v[128:129], v[130:131], v[128:129]
	v_pk_add_f32 v[130:131], v[242:243], v[154:155]
	s_nop 0
	v_pk_add_f32 v[128:129], v[130:131], v[128:129]
	v_pk_add_f32 v[130:131], v[156:157], v[140:141]
	s_nop 0
	v_pk_add_f32 v[128:129], v[130:131], v[128:129]
	v_pk_add_f32 v[130:131], v[158:159], v[142:143]
	s_nop 0
	v_pk_add_f32 v[128:129], v[130:131], v[128:129]
	s_nop 0
	v_add_f32_e32 v231, v128, v129
	v_fmac_f32_e32 v231, v226, v202
	ds_read_b64_tr_b16 v[128:129], v225 offset:17408
	ds_read_b64_tr_b16 v[130:131], v225 offset:19968
	ds_read_b64_tr_b16 v[138:139], v225 offset:20032
	ds_read_b64_tr_b16 v[136:137], v225 offset:17472
	v_cvt_pk_bf16_f32 v132, v232, v233
	v_cvt_pk_bf16_f32 v133, v146, v147
	v_cvt_pk_bf16_f32 v134, v236, v237
	v_cvt_pk_bf16_f32 v135, v150, v151
	s_waitcnt lgkmcnt(2)
; template <int NS, int SI>
; __device__ __forceinline__ void attn_stream(const unsigned char* kbase, const unsigned char* vbase, const unsigned char* q_rd, bool mask_tail, int last_valid, int hh, float sc,
;                                             f32x16 (&O)[4], float& mrun, float& lrun) {
;     ...
;     __builtin_amdgcn_sched_barrier(0);
;     PV_GROUP(S0, 0, 0) PV_GROUP(S0, 0, 1) PV_GROUP(S1, 1, 0) PV_GROUP(S1, 1, 1)
; template <int NS>
; __device__ __forceinline__ void attn_unit(const AUnit& u, unsigned char* lds, const bf16_t* __restrict__ GT, bf16_t* BRc, float sc, float lam, const float* __restrict__ subln) {
;     ...
;             if (more) { attn_store1(nb, A_KRS, rk); attn_load1(u.vb, u.ld, t + 1, rk); }
;             if (work) attn_stream<NS, 1>(kbase, vbase, q_rd, mask_tail, u.last_valid, hh, sc, O1, m1, l1r);
	s_nop 0
	v_mfma_f32_32x32x16_bf16 v[64:79], v[128:131], v[132:135], v[64:79]
	s_waitcnt lgkmcnt(0)
	v_mfma_f32_32x32x16_bf16 v[48:63], v[136:139], v[132:135], v[48:63]
	ds_read_b64_tr_b16 v[128:129], v225 offset:17536
	ds_read_b64_tr_b16 v[130:131], v225 offset:20096
	ds_read_b64_tr_b16 v[138:139], v225 offset:20160
	ds_read_b64_tr_b16 v[136:137], v225 offset:17600
	s_waitcnt lgkmcnt(2)
	v_mfma_f32_32x32x16_bf16 v[32:47], v[128:131], v[132:135], v[32:47]
	s_waitcnt lgkmcnt(0)
	v_mfma_f32_32x32x16_bf16 v[0:15], v[136:139], v[132:135], v[0:15]
	ds_read_b64_tr_b16 v[128:129], v225 offset:22528
	ds_read_b64_tr_b16 v[130:131], v225 offset:25088
	ds_read_b64_tr_b16 v[138:139], v225 offset:25152
	ds_read_b64_tr_b16 v[136:137], v225 offset:22592
	v_cvt_pk_bf16_f32 v132, v152, v153
	v_cvt_pk_bf16_f32 v133, v154, v155
	v_cvt_pk_bf16_f32 v134, v140, v141
	v_cvt_pk_bf16_f32 v135, v142, v143
	s_waitcnt lgkmcnt(2)
	s_nop 0
	v_mfma_f32_32x32x16_bf16 v[64:79], v[128:131], v[132:135], v[64:79]
	s_waitcnt lgkmcnt(0)
	v_mfma_f32_32x32x16_bf16 v[48:63], v[136:139], v[132:135], v[48:63]
	ds_read_b64_tr_b16 v[128:129], v225 offset:22656
	ds_read_b64_tr_b16 v[130:131], v225 offset:25216
	ds_read_b64_tr_b16 v[138:139], v225 offset:25280
	ds_read_b64_tr_b16 v[136:137], v225 offset:22720
	s_waitcnt lgkmcnt(2)
	v_mfma_f32_32x32x16_bf16 v[32:47], v[128:131], v[132:135], v[32:47]
	s_waitcnt lgkmcnt(0)
	v_mfma_f32_32x32x16_bf16 v[0:15], v[136:139], v[132:135], v[0:15]
	ds_read_b64_tr_b16 v[128:129], v225 offset:27648
	ds_read_b64_tr_b16 v[130:131], v225 offset:30208
	ds_read_b64_tr_b16 v[138:139], v225 offset:30272
	ds_read_b64_tr_b16 v[136:137], v225 offset:27712
	v_cvt_pk_bf16_f32 v132, v144, v145
	v_cvt_pk_bf16_f32 v133, v234, v235
	v_cvt_pk_bf16_f32 v134, v148, v149
	v_cvt_pk_bf16_f32 v135, v238, v239
	s_waitcnt lgkmcnt(2)
	s_nop 0
	v_mfma_f32_32x32x16_bf16 v[64:79], v[128:131], v[132:135], v[64:79]
	s_waitcnt lgkmcnt(0)
	v_mfma_f32_32x32x16_bf16 v[48:63], v[136:139], v[132:135], v[48:63]
	ds_read_b64_tr_b16 v[128:129], v225 offset:27776
	ds_read_b64_tr_b16 v[130:131], v225 offset:30336
	ds_read_b64_tr_b16 v[138:139], v225 offset:30400
	ds_read_b64_tr_b16 v[136:137], v225 offset:27840
	s_waitcnt lgkmcnt(2)
	v_mfma_f32_32x32x16_bf16 v[32:47], v[128:131], v[132:135], v[32:47]
	s_waitcnt lgkmcnt(0)
	v_mfma_f32_32x32x16_bf16 v[0:15], v[136:139], v[132:135], v[0:15]
	ds_read_b64_tr_b16 v[128:129], v225 offset:32768
	ds_read_b64_tr_b16 v[130:131], v225 offset:35328
	ds_read_b64_tr_b16 v[138:139], v225 offset:35392
	ds_read_b64_tr_b16 v[136:137], v225 offset:32832
	v_cvt_pk_bf16_f32 v132, v240, v241
	v_cvt_pk_bf16_f32 v133, v242, v243
	v_cvt_pk_bf16_f32 v134, v156, v157
	v_cvt_pk_bf16_f32 v135, v158, v159
	s_waitcnt lgkmcnt(2)
	s_nop 0
	v_mfma_f32_32x32x16_bf16 v[64:79], v[128:131], v[132:135], v[64:79]
	s_waitcnt lgkmcnt(0)
	v_mfma_f32_32x32x16_bf16 v[48:63], v[136:139], v[132:135], v[48:63]
	ds_read_b64_tr_b16 v[128:129], v225 offset:32896
	ds_read_b64_tr_b16 v[130:131], v225 offset:35456
	ds_read_b64_tr_b16 v[138:139], v225 offset:35520
	ds_read_b64_tr_b16 v[136:137], v225 offset:32960
	s_waitcnt lgkmcnt(2)
	v_mfma_f32_32x32x16_bf16 v[32:47], v[128:131], v[132:135], v[32:47]
	s_waitcnt lgkmcnt(0)
	v_mfma_f32_32x32x16_bf16 v[0:15], v[136:139], v[132:135], v[0:15]
	ds_read_b128 v[144:147], v222 offset:128
	ds_read_b128 v[232:235], v230 offset:160
	ds_read_b128 v[236:239], v222 offset:160
	ds_read_b128 v[148:151], v230 offset:8832
	ds_read_b128 v[240:243], v230 offset:8864
	v_mov_b32_e32 v228, v200
	v_mov_b32_e32 v226, v231

; template <int NS, int SI>
; __device__ __forceinline__ void attn_stream(const unsigned char* kbase, const unsigned char* vbase, const unsigned char* q_rd, bool mask_tail, int last_valid, int hh, float sc,
;                                             f32x16 (&O)[4], float& mrun, float& lrun) {
;     ...
;     for (int k2 = 0; k2 < 8 / NS; ++k2) {
;         const int ks = SI * (8 / NS) + k2;
;         if (k2 == 2 || k2 == 4 || k2 == 6) __builtin_amdgcn_sched_barrier(0);
;         const bf16x8 qf = *(const bf16x8*)(q_rd + ks * 32);
;         const bf16x8 k0 = *(const bf16x8*)(kbase + ks * 32);
;         const bf16x8 k1 = *(const bf16x8*)(kbase + 32 * A_KRS + ks * 32);
;         S0 = __builtin_amdgcn_mfma_f32_32x32x16_bf16(k0, qf, S0, 0, 0, 0);
;         S1 = __builtin_amdgcn_mfma_f32_32x32x16_bf16(k1, qf, S1, 0, 0, 0);
;     }
;     __builtin_amdgcn_sched_barrier(0);
;     if (mask_tail) {
;         const int thr = last_valid - 4 * hh;
; #pragma unroll
;         for (int r = 0; r < 16; ++r) { if ((r & 3) + 8 * (r >> 2) >= thr) S0[r] = -1e30f; if (32 + (r & 3) + 8 * (r >> 2) >= thr) S1[r] = -1e30f; }
;     }
.LBB0_1175:
	ds_read_b128 v[128:131], v230 offset:128
	s_waitcnt lgkmcnt(0)
	v_mfma_f32_32x32x16_bf16 v[128:143], v[128:131], v[144:147], 0
	s_waitcnt lgkmcnt(1)
	v_mfma_f32_32x32x16_bf16 v[144:159], v[148:151], v[144:147], 0
	v_mfma_f32_32x32x16_bf16 v[128:143], v[232:235], v[236:239], v[128:143]
	s_waitcnt lgkmcnt(0)
	v_mfma_f32_32x32x16_bf16 v[144:159], v[240:243], v[236:239], v[144:159]
	ds_read_b128 v[232:235], v230 offset:192
	ds_read_b128 v[236:239], v222 offset:192
	ds_read_b128 v[240:243], v230 offset:224
	ds_read_b128 v[244:247], v222 offset:224
	s_waitcnt lgkmcnt(2)
	v_mfma_f32_32x32x16_bf16 v[128:143], v[232:235], v[236:239], v[128:143]
	ds_read_b128 v[232:235], v230 offset:8896
	ds_read_b128 v[248:251], v230 offset:8928
	s_waitcnt lgkmcnt(1)
	v_mfma_f32_32x32x16_bf16 v[144:159], v[232:235], v[236:239], v[144:159]
	v_mfma_f32_32x32x16_bf16 v[128:143], v[240:243], v[244:247], v[128:143]
	s_waitcnt lgkmcnt(0)
	v_mfma_f32_32x32x16_bf16 v[144:159], v[248:251], v[244:247], v[144:159]
	s_and_b64 vcc, exec, s[42:43]
	s_cbranch_vccnz .LBB0_1177
	s_or_b64 vcc, s[40:41], s[38:39]
	s_nop 8
	v_cndmask_b32_e32 v158, v223, v158, vcc
	s_or_b64 vcc, vcc, s[36:37]
	v_cndmask_b32_e32 v157, v223, v157, vcc
	s_or_b64 vcc, vcc, s[34:35]
	v_cndmask_b32_e32 v156, v223, v156, vcc
	s_or_b64 vcc, vcc, s[30:31]
	v_cndmask_b32_e32 v155, v223, v155, vcc
	s_or_b64 vcc, vcc, s[28:29]
	v_cndmask_b32_e32 v154, v223, v154, vcc
	s_or_b64 vcc, vcc, s[26:27]
	v_cndmask_b32_e32 v153, v223, v153, vcc
	s_or_b64 vcc, vcc, s[24:25]
	v_cndmask_b32_e32 v152, v223, v152, vcc
	s_or_b64 vcc, vcc, s[22:23]
	v_cndmask_b32_e32 v151, v223, v151, vcc
	s_or_b64 vcc, vcc, s[20:21]
	v_cndmask_b32_e32 v150, v223, v150, vcc
	s_or_b64 vcc, vcc, s[18:19]
	v_cndmask_b32_e32 v149, v223, v149, vcc
	s_or_b64 vcc, vcc, s[16:17]
	v_cndmask_b32_e32 v148, v223, v148, vcc
	s_or_b64 vcc, vcc, s[14:15]
	v_cndmask_b32_e32 v147, v223, v147, vcc
	s_or_b64 vcc, vcc, s[12:13]
	v_cndmask_b32_e32 v146, v223, v146, vcc
	s_or_b64 vcc, vcc, s[10:11]
	v_cndmask_b32_e32 v145, v223, v145, vcc
	s_or_b64 vcc, vcc, s[8:9]
	v_cndmask_b32_e64 v159, v223, v159, s[40:41]
	v_cndmask_b32_e32 v144, v223, v144, vcc
